# attention: skip band mask on fully-in-window tiles; sqrelu epilogue: drop redundant canonicalize max
# baseline (speedup 1.0000x reference)
; __device__ __forceinline__ unsigned cvt_pk_bf16(float lo, float hi) { unsigned r; asm volatile("v_cvt_pk_bf16_f32 %0, %1, %2" : "=v"(r) : "v"(lo), "v"(hi)); return r; }
;     __device__ __forceinline__ void operator()(const f32x4 (&acc)[2][2][4][2], const Unit& u, int wr, int wc, int fr, int fq) const {
;         const int row0 = u.pm * BM + wr * 64 + fr, col0 = u.pn * BM + wc * 32 + 8 * fq;
; #pragma unroll
;         for (int ai = 0; ai < 2; ++ai)
; #pragma unroll
;             for (int m = 0; m < 4; ++m) { bf16_t* rowp = H + (size_t)(row0 + ai * HALF + m * 16) * DFF + col0;
; #pragma unroll
;                 for (int bj = 0; bj < 2; ++bj) { f32x4 v0 = acc[ai][bj][m][0], v1 = acc[ai][bj][m][1];
; #pragma unroll
;                     for (int e = 0; e < 4; ++e) { const float a = fmaxf(v0[e], 0.f), b = fmaxf(v1[e], 0.f); v0[e] = a * a; v1[e] = b * b; }
;                     u32x4 w; w.x = cvt_pk_bf16(v0[0], v0[1]); w.y = cvt_pk_bf16(v0[2], v0[3]); w.z = cvt_pk_bf16(v1[0], v1[1]); w.w = cvt_pk_bf16(v1[2], v1[3]);
;                     *(u32x4*)(rowp + bj * HALF) = w; } }
;     }
.LBB0_148:
	v_lshl_add_u32 v144, s54, 8, v140
	v_ashrrev_i32_e32 v145, 31, v144
	v_max_f32_e32 v120, 0, v120
	v_lshl_or_b32 v138, s81, 8, v142
	v_lshlrev_b64 v[146:147], 14, v[144:145]
	v_mul_f32_e32 v145, v120, v120
	v_max_f32_e32 v121, 0, v121
	v_max_f32_e32 v122, 0, v122
	v_ashrrev_i32_e32 v139, 31, v138
	v_max_f32_e32 v120, 0, v125
	v_mul_f32_e32 v125, v121, v121
	v_max_f32_e32 v121, v126, v126
	v_mul_f32_e32 v126, v122, v122
	v_lshl_add_u64 v[146:147], s[30:31], 0, v[146:147]
	v_lshlrev_b64 v[148:149], 1, v[138:139]
	v_max_f32_e32 v124, 0, v124
	v_mul_f32_e32 v120, v120, v120
	v_max_f32_e32 v121, 0, v121
	v_max_f32_e32 v122, 0, v127
	v_max_f32_e32 v123, 0, v123
	v_lshl_add_u64 v[138:139], v[146:147], 0, v[148:149]
	v_mul_f32_e32 v124, v124, v124
	v_mul_f32_e32 v121, v121, v121
	v_mul_f32_e32 v122, v122, v122
	v_mul_f32_e32 v123, v123, v123
	v_cvt_pk_bf16_f32 v120, v124, v120
	v_max_f32_e32 v112, 0, v112
	v_cvt_pk_bf16_f32 v121, v121, v122
	v_cvt_pk_bf16_f32 v122, v145, v125
	v_cvt_pk_bf16_f32 v123, v126, v123
	global_store_dwordx4 v[138:139], v[120:123], off
	s_nop 1
	v_max_f32_e32 v113, 0, v113
	v_max_f32_e32 v114, 0, v114
	v_mul_f32_e32 v120, v112, v112
	v_max_f32_e32 v112, 0, v117
	v_mul_f32_e32 v117, v113, v113
	v_max_f32_e32 v113, v118, v118
	v_mul_f32_e32 v118, v114, v114
	v_max_f32_e32 v116, 0, v116
	v_mul_f32_e32 v112, v112, v112
	v_max_f32_e32 v113, 0, v113
	v_max_f32_e32 v114, 0, v119
	v_max_f32_e32 v115, 0, v115
	v_mul_f32_e32 v116, v116, v116
	v_mul_f32_e32 v113, v113, v113
	v_mul_f32_e32 v114, v114, v114
	v_mul_f32_e32 v115, v115, v115
	v_cvt_pk_bf16_f32 v112, v116, v112
	v_cvt_pk_bf16_f32 v113, v113, v114
	v_cvt_pk_bf16_f32 v114, v120, v117
	v_cvt_pk_bf16_f32 v115, v118, v115
	global_store_dwordx4 v[138:139], v[112:115], off offset:256
	s_nop 1
	v_max_f32_e32 v104, 0, v104
	v_or_b32_e32 v112, 16, v144
	v_ashrrev_i32_e32 v113, 31, v112
	v_mul_f32_e32 v114, v104, v104
	v_max_f32_e32 v105, 0, v105
	v_max_f32_e32 v106, 0, v106
	v_lshlrev_b64 v[112:113], 14, v[112:113]
	v_max_f32_e32 v104, 0, v109
	v_mul_f32_e32 v109, v105, v105
	v_max_f32_e32 v105, v110, v110
	v_mul_f32_e32 v110, v106, v106
	v_lshl_add_u64 v[112:113], s[30:31], 0, v[112:113]
	v_max_f32_e32 v108, 0, v108
	v_mul_f32_e32 v104, v104, v104
	v_max_f32_e32 v105, 0, v105
	v_max_f32_e32 v106, 0, v111
	v_max_f32_e32 v107, 0, v107
	v_lshl_add_u64 v[112:113], v[112:113], 0, v[148:149]
	v_mul_f32_e32 v108, v108, v108
	v_mul_f32_e32 v105, v105, v105
	v_mul_f32_e32 v106, v106, v106
	v_mul_f32_e32 v107, v107, v107
	v_cvt_pk_bf16_f32 v104, v108, v104
	v_max_f32_e32 v96, 0, v96
	v_cvt_pk_bf16_f32 v105, v105, v106
	v_cvt_pk_bf16_f32 v106, v114, v109
	v_cvt_pk_bf16_f32 v107, v110, v107
	global_store_dwordx4 v[112:113], v[104:107], off
	s_nop 1
	v_max_f32_e32 v97, 0, v97
	v_max_f32_e32 v98, 0, v98
	v_mul_f32_e32 v104, v96, v96
	v_max_f32_e32 v96, 0, v101
	v_mul_f32_e32 v101, v97, v97
	v_max_f32_e32 v97, v102, v102
	v_mul_f32_e32 v102, v98, v98
	v_max_f32_e32 v100, 0, v100
	v_mul_f32_e32 v96, v96, v96
	v_max_f32_e32 v97, 0, v97
	v_max_f32_e32 v98, 0, v103
	v_max_f32_e32 v99, 0, v99
	v_mul_f32_e32 v100, v100, v100
	v_mul_f32_e32 v97, v97, v97
	v_mul_f32_e32 v98, v98, v98
	v_mul_f32_e32 v99, v99, v99
	v_cvt_pk_bf16_f32 v96, v100, v96
	v_cvt_pk_bf16_f32 v97, v97, v98
	v_cvt_pk_bf16_f32 v98, v104, v101
	v_cvt_pk_bf16_f32 v99, v102, v99
	global_store_dwordx4 v[112:113], v[96:99], off offset:256
	s_nop 1
	v_max_f32_e32 v88, 0, v88
	v_or_b32_e32 v96, 32, v144
	v_ashrrev_i32_e32 v97, 31, v96
	v_mul_f32_e32 v98, v88, v88
	v_max_f32_e32 v89, 0, v89
	v_max_f32_e32 v90, 0, v90
	v_lshlrev_b64 v[96:97], 14, v[96:97]
	v_max_f32_e32 v88, 0, v93
	v_mul_f32_e32 v93, v89, v89
	v_max_f32_e32 v89, v94, v94
	v_mul_f32_e32 v94, v90, v90
	v_lshl_add_u64 v[96:97], s[30:31], 0, v[96:97]
	v_max_f32_e32 v92, 0, v92
	v_mul_f32_e32 v88, v88, v88
	v_max_f32_e32 v89, 0, v89
	v_max_f32_e32 v90, 0, v95
	v_max_f32_e32 v91, 0, v91
	v_lshl_add_u64 v[96:97], v[96:97], 0, v[148:149]
	v_mul_f32_e32 v92, v92, v92
	v_mul_f32_e32 v89, v89, v89
	v_mul_f32_e32 v90, v90, v90
	v_mul_f32_e32 v91, v91, v91
	v_cvt_pk_bf16_f32 v88, v92, v88
	v_max_f32_e32 v80, 0, v80
	v_cvt_pk_bf16_f32 v89, v89, v90
	v_cvt_pk_bf16_f32 v90, v98, v93
	v_cvt_pk_bf16_f32 v91, v94, v91
	global_store_dwordx4 v[96:97], v[88:91], off
	s_nop 1
	v_max_f32_e32 v81, 0, v81
	v_max_f32_e32 v82, 0, v82
	v_mul_f32_e32 v88, v80, v80
	v_max_f32_e32 v80, 0, v85
	v_mul_f32_e32 v85, v81, v81
	v_max_f32_e32 v81, v86, v86
	v_mul_f32_e32 v86, v82, v82
	v_max_f32_e32 v84, 0, v84
	v_mul_f32_e32 v80, v80, v80
	v_max_f32_e32 v81, 0, v81
	v_max_f32_e32 v82, 0, v87
	v_max_f32_e32 v83, 0, v83
	v_mul_f32_e32 v84, v84, v84
	v_mul_f32_e32 v81, v81, v81
	v_mul_f32_e32 v82, v82, v82
	v_mul_f32_e32 v83, v83, v83
	v_cvt_pk_bf16_f32 v80, v84, v80
	v_cvt_pk_bf16_f32 v81, v81, v82
	v_cvt_pk_bf16_f32 v82, v88, v85
	v_cvt_pk_bf16_f32 v83, v86, v83
	global_store_dwordx4 v[96:97], v[80:83], off offset:256
	s_nop 1
	v_max_f32_e32 v72, 0, v72
	v_or_b32_e32 v80, 48, v144
	v_ashrrev_i32_e32 v81, 31, v80
	v_mul_f32_e32 v82, v72, v72
	v_max_f32_e32 v73, 0, v73
	v_max_f32_e32 v74, 0, v74
	v_lshlrev_b64 v[80:81], 14, v[80:81]
	v_max_f32_e32 v72, 0, v77
	v_mul_f32_e32 v77, v73, v73
	v_max_f32_e32 v73, v78, v78
	v_mul_f32_e32 v78, v74, v74
	v_lshl_add_u64 v[80:81], s[30:31], 0, v[80:81]
	v_max_f32_e32 v76, 0, v76
	v_mul_f32_e32 v72, v72, v72
	v_max_f32_e32 v73, 0, v73
	v_max_f32_e32 v74, 0, v79
	v_max_f32_e32 v75, 0, v75
	v_lshl_add_u64 v[80:81], v[80:81], 0, v[148:149]
	v_mul_f32_e32 v76, v76, v76
	v_mul_f32_e32 v73, v73, v73
	v_mul_f32_e32 v74, v74, v74
	v_mul_f32_e32 v75, v75, v75
; __device__ __forceinline__ unsigned cvt_pk_bf16(float lo, float hi) { unsigned r; asm volatile("v_cvt_pk_bf16_f32 %0, %1, %2" : "=v"(r) : "v"(lo), "v"(hi)); return r; }
;     __device__ __forceinline__ void operator()(const f32x4 (&acc)[2][2][4][2], const Unit& u, int wr, int wc, int fr, int fq) const {
;         const int row0 = u.pm * BM + wr * 64 + fr, col0 = u.pn * BM + wc * 32 + 8 * fq;
; #pragma unroll
;         for (int ai = 0; ai < 2; ++ai)
; #pragma unroll
;             for (int m = 0; m < 4; ++m) { bf16_t* rowp = H + (size_t)(row0 + ai * HALF + m * 16) * DFF + col0;
; #pragma unroll
;                 for (int bj = 0; bj < 2; ++bj) { f32x4 v0 = acc[ai][bj][m][0], v1 = acc[ai][bj][m][1];
; #pragma unroll
;                     for (int e = 0; e < 4; ++e) { const float a = fmaxf(v0[e], 0.f), b = fmaxf(v1[e], 0.f); v0[e] = a * a; v1[e] = b * b; }
;                     u32x4 w; w.x = cvt_pk_bf16(v0[0], v0[1]); w.y = cvt_pk_bf16(v0[2], v0[3]); w.z = cvt_pk_bf16(v1[0], v1[1]); w.w = cvt_pk_bf16(v1[2], v1[3]);
;                     *(u32x4*)(rowp + bj * HALF) = w; } }
;     }
	v_cvt_pk_bf16_f32 v72, v76, v72
	v_max_f32_e32 v64, 0, v64
	v_max_f32_e32 v65, 0, v65
	v_max_f32_e32 v66, 0, v66
	v_cvt_pk_bf16_f32 v73, v73, v74
	v_cvt_pk_bf16_f32 v74, v82, v77
	v_cvt_pk_bf16_f32 v75, v78, v75
	global_store_dwordx4 v[80:81], v[72:75], off
	s_nop 1
	v_mul_f32_e32 v72, v64, v64
	v_max_f32_e32 v64, v69, v69
	v_mul_f32_e32 v69, v65, v65
	v_max_f32_e32 v65, v70, v70
	v_mul_f32_e32 v70, v66, v66
	v_max_f32_e32 v64, 0, v64
	v_max_f32_e32 v65, 0, v65
	v_max_f32_e32 v66, 0, v71
	v_max_f32_e32 v68, 0, v68
	v_mul_f32_e32 v64, v64, v64
	v_mul_f32_e32 v65, v65, v65
	v_max_f32_e32 v67, 0, v67
	v_mul_f32_e32 v66, v66, v66
	v_mul_f32_e32 v68, v68, v68
	v_mul_f32_e32 v67, v67, v67
	v_cvt_pk_bf16_f32 v64, v68, v64
	v_cvt_pk_bf16_f32 v65, v65, v66
	v_cvt_pk_bf16_f32 v66, v72, v69
	v_max_f32_e32 v56, 0, v56
	v_cvt_pk_bf16_f32 v67, v70, v67
	global_store_dwordx4 v[80:81], v[64:67], off offset:256
	s_nop 1
	v_max_f32_e32 v57, 0, v57
	v_mul_f32_e32 v66, v56, v56
	v_max_f32_e32 v58, 0, v58
	v_max_f32_e32 v60, 0, v60
	v_max_f32_e32 v56, 0, v61
	v_mul_f32_e32 v61, v57, v57
	v_max_f32_e32 v57, v62, v62
	v_mul_f32_e32 v62, v58, v58
	v_mul_f32_e32 v60, v60, v60
	v_mul_f32_e32 v56, v56, v56
	v_max_f32_e32 v57, 0, v57
	v_max_f32_e32 v58, 0, v63
	s_mov_b32 s45, 0x200000
	v_mul_f32_e32 v57, v57, v57
	v_max_f32_e32 v59, 0, v59
	v_mul_f32_e32 v58, v58, v58
	v_cvt_pk_bf16_f32 v56, v60, v56
	v_add_co_u32_e32 v60, vcc, s45, v138
	v_mul_f32_e32 v59, v59, v59
	v_cvt_pk_bf16_f32 v57, v57, v58
	v_cvt_pk_bf16_f32 v58, v66, v61
	v_addc_co_u32_e32 v61, vcc, 0, v139, vcc
	v_max_f32_e32 v48, 0, v48
	v_max_f32_e32 v49, 0, v49
	v_max_f32_e32 v50, 0, v50
	v_cvt_pk_bf16_f32 v59, v62, v59
	global_store_dwordx4 v[60:61], v[56:59], off
	s_nop 1
	v_mul_f32_e32 v56, v48, v48
	v_max_f32_e32 v48, v53, v53
	v_mul_f32_e32 v53, v49, v49
	v_max_f32_e32 v49, v54, v54
	v_mul_f32_e32 v54, v50, v50
	v_max_f32_e32 v48, 0, v48
	v_max_f32_e32 v49, 0, v49
	v_max_f32_e32 v50, 0, v55
	s_mov_b64 s[60:61], 0x200000
	v_max_f32_e32 v52, 0, v52
	v_mul_f32_e32 v48, v48, v48
	v_mul_f32_e32 v49, v49, v49
	v_max_f32_e32 v51, 0, v51
	v_mul_f32_e32 v50, v50, v50
	v_lshl_add_u64 v[64:65], v[138:139], 0, s[60:61]
	v_mul_f32_e32 v52, v52, v52
	v_mul_f32_e32 v51, v51, v51
	v_cvt_pk_bf16_f32 v48, v52, v48
	v_cvt_pk_bf16_f32 v49, v49, v50
	v_cvt_pk_bf16_f32 v50, v56, v53
	v_max_f32_e32 v40, 0, v40
	v_cvt_pk_bf16_f32 v51, v54, v51
	global_store_dwordx4 v[64:65], v[48:51], off offset:256
	s_nop 1
	v_max_f32_e32 v41, 0, v41
	v_mul_f32_e32 v50, v40, v40
	v_max_f32_e32 v42, 0, v42
	v_max_f32_e32 v44, 0, v44
	v_max_f32_e32 v40, 0, v45
	v_mul_f32_e32 v45, v41, v41
	v_max_f32_e32 v41, v46, v46
	v_mul_f32_e32 v46, v42, v42
	v_mul_f32_e32 v44, v44, v44
	v_mul_f32_e32 v40, v40, v40
	v_max_f32_e32 v41, 0, v41
	v_max_f32_e32 v42, 0, v47
	s_mov_b32 s45, 0x240000
	v_mul_f32_e32 v41, v41, v41
	v_max_f32_e32 v43, 0, v43
	v_mul_f32_e32 v42, v42, v42
	v_cvt_pk_bf16_f32 v40, v44, v40
	v_add_co_u32_e32 v44, vcc, s45, v138
	v_mul_f32_e32 v43, v43, v43
	v_cvt_pk_bf16_f32 v41, v41, v42
	v_cvt_pk_bf16_f32 v42, v50, v45
	v_addc_co_u32_e32 v45, vcc, 0, v139, vcc
	v_max_f32_e32 v32, 0, v32
	v_max_f32_e32 v33, 0, v33
	v_max_f32_e32 v34, 0, v34
	v_cvt_pk_bf16_f32 v43, v46, v43
	global_store_dwordx4 v[44:45], v[40:43], off
	s_nop 1
	v_mul_f32_e32 v40, v32, v32
	v_max_f32_e32 v32, v37, v37
	v_mul_f32_e32 v37, v33, v33
	v_max_f32_e32 v33, v38, v38
	v_mul_f32_e32 v38, v34, v34
	v_max_f32_e32 v32, 0, v32
	v_max_f32_e32 v33, 0, v33
	v_max_f32_e32 v34, 0, v39
	s_mov_b64 s[60:61], 0x240000
	v_max_f32_e32 v36, 0, v36
	v_mul_f32_e32 v32, v32, v32
; __device__ __forceinline__ unsigned cvt_pk_bf16(float lo, float hi) { unsigned r; asm volatile("v_cvt_pk_bf16_f32 %0, %1, %2" : "=v"(r) : "v"(lo), "v"(hi)); return r; }
; #define PG8_BAR __builtin_amdgcn_s_barrier()
;     __device__ __forceinline__ void operator()(const f32x4 (&acc)[2][2][4][2], const Unit& u, int wr, int wc, int fr, int fq) const {
;         const int row0 = u.pm * BM + wr * 64 + fr, col0 = u.pn * BM + wc * 32 + 8 * fq;
; #pragma unroll
;         for (int ai = 0; ai < 2; ++ai)
; #pragma unroll
;             for (int m = 0; m < 4; ++m) { bf16_t* rowp = H + (size_t)(row0 + ai * HALF + m * 16) * DFF + col0;
; #pragma unroll
;                 for (int bj = 0; bj < 2; ++bj) { f32x4 v0 = acc[ai][bj][m][0], v1 = acc[ai][bj][m][1];
; #pragma unroll
;                     for (int e = 0; e < 4; ++e) { const float a = fmaxf(v0[e], 0.f), b = fmaxf(v1[e], 0.f); v0[e] = a * a; v1[e] = b * b; }
;                     u32x4 w; w.x = cvt_pk_bf16(v0[0], v0[1]); w.y = cvt_pk_bf16(v0[2], v0[3]); w.z = cvt_pk_bf16(v1[0], v1[1]); w.w = cvt_pk_bf16(v1[2], v1[3]);
;                     *(u32x4*)(rowp + bj * HALF) = w; } }
;     }
; template <class Epi, class Sched, bool ALIGN_EPI = false, bool SP2 = false>
; __device__ __forceinline__ void gemm_phase(PG8_LAS unsigned char* lds, const Gemm g, const Sched& S, const Epi& E) {
;     ...
;         if (!has_next) break;
; #pragma unroll
;         for (int a = 0; a < 2; ++a)
; #pragma unroll
;             for (int b = 0; b < 2; ++b)
; #pragma unroll
;                 for (int m = 0; m < 4; ++m)
; #pragma unroll
;                     for (int n = 0; n < 2; ++n) acc[a][b][m][n] = (f32x4){0.f, 0.f, 0.f, 0.f};
;         cur = nxt; cA = nA; cB = nB; ++ui;
;         if constexpr (ALIGN_EPI) { if (wr == 1) PG8_BAR; }
	v_mul_f32_e32 v33, v33, v33
	v_max_f32_e32 v35, 0, v35
	v_mul_f32_e32 v34, v34, v34
	v_lshl_add_u64 v[48:49], v[138:139], 0, s[60:61]
	v_mul_f32_e32 v36, v36, v36
	v_mul_f32_e32 v35, v35, v35
	v_cvt_pk_bf16_f32 v32, v36, v32
	v_cvt_pk_bf16_f32 v33, v33, v34
	v_cvt_pk_bf16_f32 v34, v40, v37
	v_max_f32_e32 v24, 0, v24
	v_cvt_pk_bf16_f32 v35, v38, v35
	global_store_dwordx4 v[48:49], v[32:35], off offset:256
	s_nop 1
	v_max_f32_e32 v25, 0, v25
	v_mul_f32_e32 v34, v24, v24
	v_max_f32_e32 v26, 0, v26
	v_max_f32_e32 v28, 0, v28
	v_max_f32_e32 v24, 0, v29
	v_mul_f32_e32 v29, v25, v25
	v_max_f32_e32 v25, v30, v30
	v_mul_f32_e32 v30, v26, v26
	v_mul_f32_e32 v28, v28, v28
	v_mul_f32_e32 v24, v24, v24
	v_max_f32_e32 v25, 0, v25
	v_max_f32_e32 v26, 0, v31
	s_mov_b32 s45, 0x280000
	v_mul_f32_e32 v25, v25, v25
	v_max_f32_e32 v27, 0, v27
	v_mul_f32_e32 v26, v26, v26
	v_cvt_pk_bf16_f32 v24, v28, v24
	v_add_co_u32_e32 v28, vcc, s45, v138
	v_mul_f32_e32 v27, v27, v27
	v_cvt_pk_bf16_f32 v25, v25, v26
	v_cvt_pk_bf16_f32 v26, v34, v29
	v_addc_co_u32_e32 v29, vcc, 0, v139, vcc
	v_max_f32_e32 v16, 0, v16
	v_max_f32_e32 v17, 0, v17
	v_max_f32_e32 v18, 0, v18
	v_cvt_pk_bf16_f32 v27, v30, v27
	global_store_dwordx4 v[28:29], v[24:27], off
	s_nop 1
	v_mul_f32_e32 v24, v16, v16
	v_max_f32_e32 v16, v21, v21
	v_mul_f32_e32 v21, v17, v17
	v_max_f32_e32 v17, v22, v22
	v_mul_f32_e32 v22, v18, v18
	v_max_f32_e32 v16, 0, v16
	v_max_f32_e32 v17, 0, v17
	v_max_f32_e32 v18, 0, v23
	s_mov_b64 s[60:61], 0x280000
	v_max_f32_e32 v20, 0, v20
	v_mul_f32_e32 v16, v16, v16
	v_mul_f32_e32 v17, v17, v17
	v_max_f32_e32 v19, 0, v19
	v_mul_f32_e32 v18, v18, v18
	v_lshl_add_u64 v[32:33], v[138:139], 0, s[60:61]
	v_mul_f32_e32 v20, v20, v20
	v_mul_f32_e32 v19, v19, v19
	v_cvt_pk_bf16_f32 v16, v20, v16
	v_cvt_pk_bf16_f32 v17, v17, v18
	v_cvt_pk_bf16_f32 v18, v24, v21
	v_max_f32_e32 v8, 0, v8
	v_cvt_pk_bf16_f32 v19, v22, v19
	global_store_dwordx4 v[32:33], v[16:19], off offset:256
	s_nop 1
	v_max_f32_e32 v9, 0, v9
	v_mul_f32_e32 v18, v8, v8
	v_max_f32_e32 v10, 0, v10
	v_max_f32_e32 v12, 0, v12
	v_max_f32_e32 v8, 0, v13
	v_mul_f32_e32 v13, v9, v9
	v_max_f32_e32 v9, v14, v14
	v_mul_f32_e32 v14, v10, v10
	v_mul_f32_e32 v12, v12, v12
	v_mul_f32_e32 v8, v8, v8
	v_max_f32_e32 v9, 0, v9
	v_max_f32_e32 v10, 0, v15
	s_mov_b32 s45, 0x2c0000
	v_mul_f32_e32 v9, v9, v9
	v_max_f32_e32 v11, 0, v11
	v_mul_f32_e32 v10, v10, v10
	v_cvt_pk_bf16_f32 v8, v12, v8
	v_add_co_u32_e32 v12, vcc, s45, v138
	v_mul_f32_e32 v11, v11, v11
	v_cvt_pk_bf16_f32 v9, v9, v10
	v_cvt_pk_bf16_f32 v10, v18, v13
	v_addc_co_u32_e32 v13, vcc, 0, v139, vcc
	v_max_f32_e32 v0, 0, v0
	v_max_f32_e32 v1, 0, v1
	v_max_f32_e32 v2, 0, v2
	v_cvt_pk_bf16_f32 v11, v14, v11
	global_store_dwordx4 v[12:13], v[8:11], off
	s_nop 1
	s_mov_b64 s[60:61], 0x2c0000
	v_mul_f32_e32 v8, v0, v0
	v_max_f32_e32 v0, v5, v5
	v_mul_f32_e32 v5, v1, v1
	v_max_f32_e32 v1, v6, v6
	v_mul_f32_e32 v6, v2, v2
	v_max_f32_e32 v0, 0, v0
	v_max_f32_e32 v1, 0, v1
	v_max_f32_e32 v2, 0, v7
	v_max_f32_e32 v3, 0, v3
	v_lshl_add_u64 v[16:17], v[138:139], 0, s[60:61]
	v_max_f32_e32 v4, 0, v4
	v_mul_f32_e32 v0, v0, v0
	v_mul_f32_e32 v1, v1, v1
	v_mul_f32_e32 v2, v2, v2
	v_mul_f32_e32 v3, v3, v3
	s_andn2_b64 vcc, exec, s[42:43]
	s_mov_b64 s[42:43], -1
	v_readlane_b32 s84, v254, 57
	v_mul_f32_e32 v4, v4, v4
	v_cvt_pk_bf16_f32 v0, v4, v0
	v_cvt_pk_bf16_f32 v1, v1, v2
	v_cvt_pk_bf16_f32 v2, v8, v5
	v_cvt_pk_bf16_f32 v3, v6, v3
	global_store_dwordx4 v[16:17], v[0:3], off offset:256
	s_nop 1
	s_cbranch_vccnz .LBB0_141
	s_andn2_b64 vcc, exec, s[16:17]
	s_cbranch_vccnz .LBB0_140
	s_barrier
	s_branch .LBB0_140

; #define LAS __attribute__((address_space(3)))
; __device__ __forceinline__ int crow(int r, int hi) { return (r & 3) + 8 * (r >> 2) + 4 * hi; }
; __device__ __forceinline__ void attn_unit(LAS unsigned char* lds, bf16_t* Y, const bf16_t* KB, const bf16_t* VT, const float* sink, int b, int kvh, int qb, bool isctx) {
;     ...
;                 for (int ks = 0; ks < 4; ++ks) { const bf16x8 kf = *(const LAS bf16x8*)(Ks + ((32 * kb + r32) * 72 + 16 * ks + 8 * hi) * 2);
;                     s[kb] = __builtin_amdgcn_mfma_f32_32x32x16_bf16(kf, qf[j][ks], s[kb], 0, 0, 0); }
;             if (it < ntl) { const int ks0 = qb * 128 - 128 + 64 * it;
; #pragma unroll
;                 for (int kb = 0; kb < 2; ++kb)
; #pragma unroll
;                     for (int r = 0; r < 16; ++r) { const int dk = (tq0 + 32 * j + r32) - (ks0 + 32 * kb + crow(r, hi)); if (dk > 128 || dk < -128) s[kb][r] = -1e30f; } }
.LBB0_254:
	v_add_u32_e32 v64, s67, v142
	v_add_u32_e32 v178, v64, v153
	ds_read_b128 v[64:67], v178
	ds_read_b128 v[68:71], v178 offset:32
	s_cmp_lt_i32 s66, 6
	s_cselect_b64 s[46:47], -1, 0
	s_cmp_gt_i32 s66, 5
	s_waitcnt lgkmcnt(1)
	v_mfma_f32_32x32x16_bf16 v[80:95], v[64:67], v[96:99], 0
	ds_read_b128 v[64:67], v178 offset:64
	ds_read_b128 v[174:177], v178 offset:4640
	s_waitcnt lgkmcnt(2)
	v_mfma_f32_32x32x16_bf16 v[80:95], v[68:71], v[100:103], v[80:95]
	s_waitcnt lgkmcnt(1)
	v_mfma_f32_32x32x16_bf16 v[80:95], v[64:67], v[104:107], v[80:95]
	ds_read_b128 v[64:67], v178 offset:96
	s_waitcnt lgkmcnt(0)
	v_mfma_f32_32x32x16_bf16 v[80:95], v[64:67], v[108:111], v[80:95]
	ds_read_b128 v[64:67], v178 offset:4608
	s_waitcnt lgkmcnt(0)
	v_mfma_f32_32x32x16_bf16 v[64:79], v[64:67], v[96:99], 0
	v_mfma_f32_32x32x16_bf16 v[64:79], v[174:177], v[100:103], v[64:79]
	ds_read_b128 v[174:177], v178 offset:4672
	s_waitcnt lgkmcnt(0)
	v_mfma_f32_32x32x16_bf16 v[64:79], v[174:177], v[104:107], v[64:79]
	ds_read_b128 v[174:177], v178 offset:4704
	s_waitcnt lgkmcnt(0)
	v_mfma_f32_32x32x16_bf16 v[64:79], v[174:177], v[108:111], v[64:79]
	v_subrev_u32_e32 v175, s63, v169
	s_cbranch_scc1 .LBB0_256
	v_readfirstlane_b32 s98, v242
	s_bfe_u32 s98, s98, 0x10006
	s_sub_i32 s99, s66, s98
	s_add_i32 s99, s99, -1
	s_cmp_lt_u32 s99, 3
	s_cbranch_scc1 .LBB0_256
	v_add_u32_e32 v173, v175, v152
	v_cmp_gt_u32_e32 vcc, s94, v173
	v_add_u32_e32 v173, v175, v154
	s_nop 0
	v_cndmask_b32_e32 v80, v80, v245, vcc
	v_cmp_lt_u32_e32 vcc, s20, v173
	v_add_u32_e32 v173, v175, v155
	s_nop 0
	v_cndmask_b32_e32 v81, v245, v81, vcc
	v_cmp_lt_u32_e32 vcc, s20, v173
	v_add_u32_e32 v173, v175, v156
	s_nop 0
	v_cndmask_b32_e32 v82, v245, v82, vcc
	v_cmp_lt_u32_e32 vcc, s20, v173
	v_add_u32_e32 v173, v175, v157
	s_nop 0
	v_cndmask_b32_e32 v83, v245, v83, vcc
	v_cmp_lt_u32_e32 vcc, s20, v173
	v_add_u32_e32 v173, v175, v158
	s_nop 0
	v_cndmask_b32_e32 v84, v245, v84, vcc
	v_cmp_lt_u32_e32 vcc, s20, v173
	v_add_u32_e32 v173, v175, v159
	s_nop 0
	v_cndmask_b32_e32 v85, v245, v85, vcc
	v_cmp_lt_u32_e32 vcc, s20, v173
	v_add_u32_e32 v173, v175, v160
	s_nop 0
	v_cndmask_b32_e32 v86, v245, v86, vcc
	v_cmp_lt_u32_e32 vcc, s20, v173
	v_add_u32_e32 v173, v175, v161
	s_nop 0
	v_cndmask_b32_e32 v87, v245, v87, vcc
	v_cmp_lt_u32_e32 vcc, s20, v173
	v_add_u32_e32 v173, v175, v162
	s_nop 0
	v_cndmask_b32_e32 v88, v245, v88, vcc
	v_cmp_lt_u32_e32 vcc, s20, v173
	v_add_u32_e32 v173, v175, v163
	s_nop 0
	v_cndmask_b32_e32 v89, v245, v89, vcc
	v_cmp_lt_u32_e32 vcc, s20, v173
	v_add_u32_e32 v173, v175, v164
	s_nop 0
	v_cndmask_b32_e32 v90, v245, v90, vcc
	v_cmp_lt_u32_e32 vcc, s20, v173
	v_add_u32_e32 v173, v175, v165
	s_nop 0
	v_cndmask_b32_e32 v91, v245, v91, vcc
	v_cmp_lt_u32_e32 vcc, s20, v173
	v_add_u32_e32 v173, v175, v166
	s_nop 0
	v_cndmask_b32_e32 v92, v245, v92, vcc
	v_cmp_lt_u32_e32 vcc, s20, v173
	v_add_u32_e32 v173, v175, v167
	s_nop 0
	v_cndmask_b32_e32 v93, v245, v93, vcc
	v_cmp_lt_u32_e32 vcc, s20, v173
	v_add_u32_e32 v173, v175, v168
	s_nop 0
	v_cndmask_b32_e32 v94, v245, v94, vcc
	v_cmp_lt_u32_e32 vcc, s20, v173
	v_subrev_u32_e32 v173, s63, v170
	v_add_u32_e32 v174, v173, v152
	v_cndmask_b32_e32 v95, v245, v95, vcc
	v_cmp_lt_u32_e32 vcc, s20, v174
	v_add_u32_e32 v174, v173, v154
	s_nop 0
	v_cndmask_b32_e32 v64, v245, v64, vcc
	v_cmp_lt_u32_e32 vcc, s20, v174
	v_add_u32_e32 v174, v173, v155
	s_nop 0
	v_cndmask_b32_e32 v65, v245, v65, vcc
	v_cmp_lt_u32_e32 vcc, s20, v174
	v_add_u32_e32 v174, v173, v156
	s_nop 0
	v_cndmask_b32_e32 v66, v245, v66, vcc
	v_cmp_lt_u32_e32 vcc, s20, v174
	v_add_u32_e32 v174, v173, v157
	s_nop 0
	v_cndmask_b32_e32 v67, v245, v67, vcc
	v_cmp_lt_u32_e32 vcc, s20, v174
	v_add_u32_e32 v174, v173, v158
	s_nop 0
	v_cndmask_b32_e32 v68, v245, v68, vcc
	v_cmp_lt_u32_e32 vcc, s20, v174
	v_add_u32_e32 v174, v173, v159
	s_nop 0
	v_cndmask_b32_e32 v69, v245, v69, vcc
	v_cmp_lt_u32_e32 vcc, s20, v174
	v_add_u32_e32 v174, v173, v160
	s_nop 0
	v_cndmask_b32_e32 v70, v245, v70, vcc
	v_cmp_lt_u32_e32 vcc, s20, v174
	v_add_u32_e32 v174, v173, v161
	s_nop 0
	v_cndmask_b32_e32 v71, v245, v71, vcc
	v_cmp_lt_u32_e32 vcc, s20, v174
	v_add_u32_e32 v174, v173, v162
	s_nop 0
	v_cndmask_b32_e32 v72, v245, v72, vcc
	v_cmp_lt_u32_e32 vcc, s20, v174
	v_add_u32_e32 v174, v173, v163
	s_nop 0
	v_cndmask_b32_e32 v73, v245, v73, vcc
	v_cmp_lt_u32_e32 vcc, s20, v174
	v_add_u32_e32 v174, v173, v164
	s_nop 0
	v_cndmask_b32_e32 v74, v245, v74, vcc
	v_cmp_lt_u32_e32 vcc, s20, v174
	v_add_u32_e32 v174, v173, v165
	s_nop 0
	v_cndmask_b32_e32 v75, v245, v75, vcc
	v_cmp_lt_u32_e32 vcc, s20, v174
	v_add_u32_e32 v174, v173, v166
	s_nop 0
	v_cndmask_b32_e32 v76, v245, v76, vcc
	v_cmp_lt_u32_e32 vcc, s20, v174
	v_add_u32_e32 v174, v173, v167
	v_add_u32_e32 v173, v173, v168
	v_cndmask_b32_e32 v77, v245, v77, vcc
	v_cmp_lt_u32_e32 vcc, s20, v174
	s_nop 1
	v_cndmask_b32_e32 v78, v245, v78, vcc
	v_cmp_lt_u32_e32 vcc, s20, v173
	s_nop 1
	v_cndmask_b32_e32 v79, v245, v79, vcc
; __device__ __forceinline__ unsigned cvt_pk_bf16(float lo, float hi) { unsigned r; asm volatile("v_cvt_pk_bf16_f32 %0, %1, %2" : "=v"(r) : "v"(lo), "v"(hi)); return r; }
; #define LAS __attribute__((address_space(3)))
; __device__ __forceinline__ void attn_unit(LAS unsigned char* lds, bf16_t* Y, const bf16_t* KB, const bf16_t* VT, const float* sink, int b, int kvh, int qb, bool isctx) {
;     ...
;             float mx = s[0][0];
; #pragma unroll
;             for (int kb = 0; kb < 2; ++kb)
; #pragma unroll
;                 for (int r = 0; r < 16; ++r) mx = fmaxf(mx, s[kb][r]);
;             mx = fmaxf(mx, __shfl_xor(mx, 32));
;             const float mnew = fmaxf(mx_[j], mx), alpha = __builtin_amdgcn_exp2f(mx_[j] - mnew); mx_[j] = mnew;
;             float ls = 0.f;
; #pragma unroll
;             for (int kb = 0; kb < 2; ++kb)
; #pragma unroll
;                 for (int r = 0; r < 16; ++r) { const float pv = __builtin_amdgcn_exp2f(s[kb][r] - mnew); s[kb][r] = pv; ls += pv; }
;             l_[j] = l_[j] * alpha + ls;
; #pragma unroll
;             for (int d = 0; d < 2; ++d)
; #pragma unroll
;                 for (int r = 0; r < 16; ++r) o[j][d][r] *= alpha;
; #pragma unroll
;             for (int kk = 0; kk < 4; ++kk) { const int kb = kk >> 1, jj = kk & 1; u32x4 w;
;                 w.x = cvt_pk_bf16(s[kb][8 * jj + 0], s[kb][8 * jj + 1]); w.y = cvt_pk_bf16(s[kb][8 * jj + 2], s[kb][8 * jj + 3]);
;                 w.z = cvt_pk_bf16(s[kb][8 * jj + 4], s[kb][8 * jj + 5]); w.w = cvt_pk_bf16(s[kb][8 * jj + 6], s[kb][8 * jj + 7]);
;                 pf[kk] = __builtin_bit_cast(bf16x8, w); }
; #pragma unroll
;             for (int d = 0; d < 2; ++d)
; #pragma unroll
;                 for (int kk = 0; kk < 4; ++kk) { const int kb = kk >> 1, jj = kk & 1;
;                     const LAS unsigned char* vp = Vs + ((32 * d + r32) * 72 + 32 * kb + 16 * jj + 4 * hi) * 2;
;                     const u32x2 lo = *(const LAS u32x2*)vp, hh = *(const LAS u32x2*)(vp + 16);
;                     const u32x4 w = {lo.x, lo.y, hh.x, hh.y}; const bf16x8 vf = __builtin_bit_cast(bf16x8, w);
;                     o[j][d] = __builtin_amdgcn_mfma_f32_32x32x16_bf16(vf, pf[kk], o[j][d], 0, 0, 0); }
.LBB0_256:
	v_max_f32_e32 v173, v81, v81
	v_max_f32_e32 v174, v80, v80
	v_max_f32_e32 v173, v174, v173
	v_max3_f32 v173, v173, v82, v83
	v_max3_f32 v173, v173, v84, v85
	v_max3_f32 v173, v173, v86, v87
	v_max3_f32 v173, v173, v88, v89
	v_max3_f32 v173, v173, v90, v91
	v_max3_f32 v173, v173, v92, v93
	v_max3_f32 v173, v173, v94, v95
	v_max3_f32 v173, v173, v64, v65
	v_max3_f32 v173, v173, v66, v67
	v_max3_f32 v173, v173, v68, v69
	v_max3_f32 v173, v173, v70, v71
	v_max3_f32 v173, v173, v72, v73
	v_max3_f32 v173, v173, v74, v75
	v_max3_f32 v173, v173, v76, v77
	v_max3_f32 v173, v173, v78, v79
	ds_bpermute_b32 v174, v149, v173
	v_add_u32_e32 v176, s67, v140
	s_andn2_b64 vcc, exec, s[46:47]
	s_waitcnt lgkmcnt(0)
	v_max3_f32 v173, v148, v173, v174
	v_sub_f32_e32 v80, v80, v173
	v_sub_f32_e32 v64, v64, v173
	v_exp_f32_e32 v179, v80
	v_sub_f32_e32 v80, v81, v173
	v_exp_f32_e32 v199, v64
	v_sub_f32_e32 v64, v65, v173
	v_exp_f32_e32 v181, v80
	v_sub_f32_e32 v80, v82, v173
	v_exp_f32_e32 v200, v64
	v_sub_f32_e32 v64, v66, v173
	v_exp_f32_e32 v183, v80
	v_sub_f32_e32 v80, v83, v173
	v_exp_f32_e32 v201, v64
	v_sub_f32_e32 v64, v67, v173
	v_exp_f32_e32 v185, v80
	v_sub_f32_e32 v80, v84, v173
	v_exp_f32_e32 v202, v64
	v_sub_f32_e32 v64, v68, v173
	v_exp_f32_e32 v187, v80
	v_sub_f32_e32 v80, v85, v173
	v_exp_f32_e32 v203, v64
	v_sub_f32_e32 v64, v69, v173
	v_exp_f32_e32 v188, v80
	v_sub_f32_e32 v80, v86, v173
	v_exp_f32_e32 v204, v64
	v_sub_f32_e32 v64, v70, v173
	v_exp_f32_e32 v189, v80
	v_sub_f32_e32 v80, v87, v173
	v_exp_f32_e32 v205, v64
	v_sub_f32_e32 v64, v71, v173
	v_exp_f32_e32 v190, v80
	v_sub_f32_e32 v80, v88, v173
	v_exp_f32_e32 v206, v64
	v_sub_f32_e32 v64, v72, v173
	v_exp_f32_e32 v191, v80
	v_sub_f32_e32 v80, v89, v173
	v_exp_f32_e32 v207, v64
	v_sub_f32_e32 v64, v73, v173
	v_exp_f32_e32 v192, v80
	v_sub_f32_e32 v80, v90, v173
	v_exp_f32_e32 v212, v64
	v_sub_f32_e32 v64, v74, v173
	v_exp_f32_e32 v193, v80
	v_sub_f32_e32 v80, v91, v173
	v_exp_f32_e32 v213, v64
	v_sub_f32_e32 v64, v75, v173
	v_exp_f32_e32 v194, v80
	v_sub_f32_e32 v80, v92, v173
	v_exp_f32_e32 v180, v64
	v_sub_f32_e32 v64, v76, v173
	v_exp_f32_e32 v195, v80
	v_sub_f32_e32 v80, v93, v173
	v_exp_f32_e32 v182, v64
	v_sub_f32_e32 v64, v77, v173
	v_sub_f32_e32 v148, v148, v173
	v_exp_f32_e32 v196, v80
	v_sub_f32_e32 v80, v94, v173
	v_exp_f32_e32 v184, v64
	v_sub_f32_e32 v64, v78, v173
	v_add_u32_e32 v88, v176, v153
	v_exp_f32_e32 v197, v80
	v_sub_f32_e32 v80, v95, v173
	v_exp_f32_e32 v186, v64
	v_sub_f32_e32 v64, v79, v173
	v_exp_f32_e32 v148, v148
	v_add_u32_e32 v176, 0x2000, v88
	v_exp_f32_e32 v198, v80
	v_exp_f32_e32 v174, v64
	v_cvt_pk_bf16_f32 v64, v179, v181
	v_cvt_pk_bf16_f32 v65, v183, v185
	v_cvt_pk_bf16_f32 v66, v187, v188
	v_cvt_pk_bf16_f32 v67, v189, v190
	v_cvt_pk_bf16_f32 v68, v191, v192
	v_cvt_pk_bf16_f32 v69, v193, v194
	v_cvt_pk_bf16_f32 v70, v195, v196
	v_cvt_pk_bf16_f32 v71, v197, v198
	v_cvt_pk_bf16_f32 v72, v199, v200
	v_cvt_pk_bf16_f32 v73, v201, v202
	v_cvt_pk_bf16_f32 v74, v203, v204
	v_cvt_pk_bf16_f32 v75, v205, v206
	v_cvt_pk_bf16_f32 v76, v207, v212
	v_cvt_pk_bf16_f32 v77, v213, v180
	v_cvt_pk_bf16_f32 v78, v182, v184
	v_cvt_pk_bf16_f32 v79, v186, v174
	ds_read2_b64 v[80:83], v176 offset0:128 offset1:130
	ds_read2_b64 v[84:87], v176 offset0:132 offset1:134
	v_pk_mul_f32 v[62:63], v[62:63], v[148:149] op_sel_hi:[1,0]
	v_pk_mul_f32 v[60:61], v[60:61], v[148:149] op_sel_hi:[1,0]
	v_pk_mul_f32 v[58:59], v[58:59], v[148:149] op_sel_hi:[1,0]
	v_pk_mul_f32 v[56:57], v[56:57], v[148:149] op_sel_hi:[1,0]
	v_pk_mul_f32 v[54:55], v[54:55], v[148:149] op_sel_hi:[1,0]
	v_pk_mul_f32 v[52:53], v[52:53], v[148:149] op_sel_hi:[1,0]
	v_pk_mul_f32 v[50:51], v[50:51], v[148:149] op_sel_hi:[1,0]
	v_pk_mul_f32 v[48:49], v[48:49], v[148:149] op_sel_hi:[1,0]
	v_add_u32_e32 v177, 0x3000, v88
	v_pk_mul_f32 v[46:47], v[46:47], v[148:149] op_sel_hi:[1,0]
	s_waitcnt lgkmcnt(1)
	v_mfma_f32_32x32x16_bf16 v[48:63], v[80:83], v[64:67], v[48:63]
	ds_read2_b64 v[80:83], v176 offset0:136 offset1:138
	v_mul_f32_e64 v44, v44, v148
	v_mul_f32_e64 v45, v45, v148
	v_mul_f32_e64 v42, v42, v148
	v_mul_f32_e64 v43, v43, v148
	v_pk_mul_f32 v[40:41], v[40:41], v[148:149] op_sel_hi:[1,0]
	v_pk_mul_f32 v[38:39], v[38:39], v[148:149] op_sel_hi:[1,0]
	v_pk_mul_f32 v[36:37], v[36:37], v[148:149] op_sel_hi:[1,0]
	v_pk_mul_f32 v[34:35], v[34:35], v[148:149] op_sel_hi:[1,0]
	s_waitcnt lgkmcnt(1)
	v_mfma_f32_32x32x16_bf16 v[48:63], v[84:87], v[68:71], v[48:63]
	v_mul_f32_e64 v32, v32, v148
	v_mul_f32_e64 v33, v33, v148
	s_waitcnt lgkmcnt(0)
	v_mfma_f32_32x32x16_bf16 v[48:63], v[80:83], v[72:75], v[48:63]
	ds_read2_b64 v[80:83], v176 offset0:140 offset1:142
	s_waitcnt lgkmcnt(0)
	v_mfma_f32_32x32x16_bf16 v[48:63], v[80:83], v[76:79], v[48:63]
	ds_read2_b64 v[80:83], v177 offset0:192 offset1:194
	s_waitcnt lgkmcnt(0)
	v_mfma_f32_32x32x16_bf16 v[32:47], v[80:83], v[64:67], v[32:47]
	ds_read2_b64 v[64:67], v177 offset0:196 offset1:198
	s_waitcnt lgkmcnt(0)
	v_mfma_f32_32x32x16_bf16 v[32:47], v[64:67], v[68:71], v[32:47]
	ds_read2_b64 v[64:67], v177 offset0:200 offset1:202
	s_waitcnt lgkmcnt(0)
	v_mfma_f32_32x32x16_bf16 v[32:47], v[64:67], v[72:75], v[32:47]
	ds_read2_b64 v[64:67], v177 offset0:204 offset1:206
	s_waitcnt lgkmcnt(0)
	v_mfma_f32_32x32x16_bf16 v[32:47], v[64:67], v[76:79], v[32:47]
	ds_read_b128 v[64:67], v178
	ds_read_b128 v[68:71], v178 offset:32
	ds_read_b128 v[218:221], v178 offset:4640
	s_waitcnt lgkmcnt(2)
	v_mfma_f32_32x32x16_bf16 v[80:95], v[64:67], v[112:115], 0
	ds_read_b128 v[64:67], v178 offset:64
	s_waitcnt lgkmcnt(2)
	v_mfma_f32_32x32x16_bf16 v[80:95], v[68:71], v[116:119], v[80:95]
	s_waitcnt lgkmcnt(0)
	v_mfma_f32_32x32x16_bf16 v[80:95], v[64:67], v[120:123], v[80:95]
	ds_read_b128 v[64:67], v178 offset:96
	s_waitcnt lgkmcnt(0)
	v_mfma_f32_32x32x16_bf16 v[80:95], v[64:67], v[124:127], v[80:95]
	ds_read_b128 v[64:67], v178 offset:4608
	s_waitcnt lgkmcnt(0)
	v_mfma_f32_32x32x16_bf16 v[64:79], v[64:67], v[112:115], 0
	v_mfma_f32_32x32x16_bf16 v[64:79], v[218:221], v[116:119], v[64:79]
	ds_read_b128 v[218:221], v178 offset:4672
	s_waitcnt lgkmcnt(0)
	v_mfma_f32_32x32x16_bf16 v[64:79], v[218:221], v[120:123], v[64:79]
	ds_read_b128 v[218:221], v178 offset:4704
	s_waitcnt lgkmcnt(0)
	v_mfma_f32_32x32x16_bf16 v[64:79], v[218:221], v[124:127], v[64:79]
	s_cbranch_vccnz .LBB0_258
; __device__ __forceinline__ int crow(int r, int hi) { return (r & 3) + 8 * (r >> 2) + 4 * hi; }
; __device__ __forceinline__ void attn_unit(LAS unsigned char* lds, bf16_t* Y, const bf16_t* KB, const bf16_t* VT, const float* sink, int b, int kvh, int qb, bool isctx) {
;     ...
;             if (it < ntl) { const int ks0 = qb * 128 - 128 + 64 * it;
; #pragma unroll
;                 for (int kb = 0; kb < 2; ++kb)
; #pragma unroll
;                     for (int r = 0; r < 16; ++r) { const int dk = (tq0 + 32 * j + r32) - (ks0 + 32 * kb + crow(r, hi)); if (dk > 128 || dk < -128) s[kb][r] = -1e30f; } }
	v_readfirstlane_b32 s98, v242
	s_bfe_u32 s98, s98, 0x10006
	s_sub_i32 s99, s66, s98
	s_add_i32 s99, s99, -1
	s_cmp_lt_u32 s99, 3
	s_cbranch_scc1 .LBB0_258
	v_subrev_u32_e32 v178, s63, v171
	v_add_u32_e32 v210, v178, v152
	v_cmp_gt_u32_e32 vcc, s94, v210
	v_add_u32_e32 v210, v178, v154
	s_nop 0
	v_cndmask_b32_e32 v80, v80, v245, vcc
	v_cmp_lt_u32_e32 vcc, s20, v210
	v_add_u32_e32 v210, v178, v155
	s_nop 0
	v_cndmask_b32_e32 v81, v245, v81, vcc
	v_cmp_lt_u32_e32 vcc, s20, v210
	v_add_u32_e32 v210, v178, v156
	s_nop 0
	v_cndmask_b32_e32 v82, v245, v82, vcc
	v_cmp_lt_u32_e32 vcc, s20, v210
	v_add_u32_e32 v210, v178, v157
	s_nop 0
	v_cndmask_b32_e32 v83, v245, v83, vcc
	v_cmp_lt_u32_e32 vcc, s20, v210
	v_add_u32_e32 v210, v178, v158
	s_nop 0
	v_cndmask_b32_e32 v84, v245, v84, vcc
	v_cmp_lt_u32_e32 vcc, s20, v210
	v_add_u32_e32 v210, v178, v159
	s_nop 0
	v_cndmask_b32_e32 v85, v245, v85, vcc
	v_cmp_lt_u32_e32 vcc, s20, v210
	v_add_u32_e32 v210, v178, v160
	s_nop 0
	v_cndmask_b32_e32 v86, v245, v86, vcc
	v_cmp_lt_u32_e32 vcc, s20, v210
	v_add_u32_e32 v210, v178, v161
	s_nop 0
	v_cndmask_b32_e32 v87, v245, v87, vcc
	v_cmp_lt_u32_e32 vcc, s20, v210
	v_add_u32_e32 v210, v178, v162
	s_nop 0
	v_cndmask_b32_e32 v88, v245, v88, vcc
	v_cmp_lt_u32_e32 vcc, s20, v210
	v_add_u32_e32 v210, v178, v163
	s_nop 0
	v_cndmask_b32_e32 v89, v245, v89, vcc
	v_cmp_lt_u32_e32 vcc, s20, v210
	v_add_u32_e32 v210, v178, v164
	s_nop 0
	v_cndmask_b32_e32 v90, v245, v90, vcc
	v_cmp_lt_u32_e32 vcc, s20, v210
	v_add_u32_e32 v210, v178, v165
	s_nop 0
	v_cndmask_b32_e32 v91, v245, v91, vcc
	v_cmp_lt_u32_e32 vcc, s20, v210
	v_add_u32_e32 v210, v178, v166
	s_nop 0
	v_cndmask_b32_e32 v92, v245, v92, vcc
	v_cmp_lt_u32_e32 vcc, s20, v210
	v_add_u32_e32 v210, v178, v167
	v_add_u32_e32 v178, v178, v168
	v_cndmask_b32_e32 v93, v245, v93, vcc
	v_cmp_lt_u32_e32 vcc, s20, v210
	s_nop 1
	v_cndmask_b32_e32 v94, v245, v94, vcc
	v_cmp_lt_u32_e32 vcc, s20, v178
	v_add_u32_e32 v178, v175, v152
	s_nop 0
	v_cndmask_b32_e32 v95, v245, v95, vcc
	v_cmp_lt_u32_e32 vcc, s20, v178
	v_add_u32_e32 v178, v175, v154
	s_nop 0
	v_cndmask_b32_e32 v64, v245, v64, vcc
	v_cmp_lt_u32_e32 vcc, s20, v178
	v_add_u32_e32 v178, v175, v155
	s_nop 0
	v_cndmask_b32_e32 v65, v245, v65, vcc
	v_cmp_lt_u32_e32 vcc, s20, v178
	v_add_u32_e32 v178, v175, v156
	s_nop 0
	v_cndmask_b32_e32 v66, v245, v66, vcc
	v_cmp_lt_u32_e32 vcc, s20, v178
	v_add_u32_e32 v178, v175, v157
	s_nop 0
	v_cndmask_b32_e32 v67, v245, v67, vcc
	v_cmp_lt_u32_e32 vcc, s20, v178
	v_add_u32_e32 v178, v175, v158
	s_nop 0
	v_cndmask_b32_e32 v68, v245, v68, vcc
	v_cmp_lt_u32_e32 vcc, s20, v178
	v_add_u32_e32 v178, v175, v159
	s_nop 0
	v_cndmask_b32_e32 v69, v245, v69, vcc
	v_cmp_lt_u32_e32 vcc, s20, v178
	v_add_u32_e32 v178, v175, v160
	s_nop 0
	v_cndmask_b32_e32 v70, v245, v70, vcc
	v_cmp_lt_u32_e32 vcc, s20, v178
	v_add_u32_e32 v178, v175, v161
	s_nop 0
	v_cndmask_b32_e32 v71, v245, v71, vcc
	v_cmp_lt_u32_e32 vcc, s20, v178
	v_add_u32_e32 v178, v175, v162
	s_nop 0
	v_cndmask_b32_e32 v72, v245, v72, vcc
	v_cmp_lt_u32_e32 vcc, s20, v178
	v_add_u32_e32 v178, v175, v163
	s_nop 0
	v_cndmask_b32_e32 v73, v245, v73, vcc
	v_cmp_lt_u32_e32 vcc, s20, v178
	v_add_u32_e32 v178, v175, v164
	s_nop 0
	v_cndmask_b32_e32 v74, v245, v74, vcc
	v_cmp_lt_u32_e32 vcc, s20, v178
	v_add_u32_e32 v178, v175, v165
	s_nop 0
	v_cndmask_b32_e32 v75, v245, v75, vcc
	v_cmp_lt_u32_e32 vcc, s20, v178
	v_add_u32_e32 v178, v175, v166
	s_nop 0
	v_cndmask_b32_e32 v76, v245, v76, vcc
	v_cmp_lt_u32_e32 vcc, s20, v178
	v_add_u32_e32 v178, v175, v167
	v_add_u32_e32 v175, v175, v168
	v_cndmask_b32_e32 v77, v245, v77, vcc
	v_cmp_lt_u32_e32 vcc, s20, v178
	s_nop 1
	v_cndmask_b32_e32 v78, v245, v78, vcc
	v_cmp_lt_u32_e32 vcc, s20, v175
	s_nop 1
	v_cndmask_b32_e32 v79, v245, v79, vcc
